# up phase prefetch: wait for the prefetched DMA before the tail stores instead of at the next header (store latency no longer waited)
# speedup vs baseline: 1.0368x; 1.0012x over previous
; DI int crow(int i, int h) { return (i & 3) + 8 * (i >> 2) + 4 * h; }
; template <int MB, class Epi>
; DI void gemm_tile(const u16* __restrict__ A, int lda, int row0, int Mrows, const u16* __restrict__ Bt, int ldb, int K, char* smem, Epi& epi, int rot) {
;     ...
;   const u16* bp = Bt + (size_t)lr * ldb + lch * 8;
;   f32x16 acc[2][MB];
; #pragma unroll
;   for (int nb = 0; nb < 2; ++nb)
; #pragma unroll
;     for (int mb = 0; mb < MB; ++mb)
; #pragma unroll
;       for (int i = 0; i < 16; ++i) acc[nb][mb][i] = 0.f;
;   const int KT = K >> 6;
;   int kcur = rot % KT;
;     ...
;   GEMM_STAGE(0)
;   asm volatile("s_waitcnt vmcnt(0)" ::: "memory");
;   __syncthreads();
;   const int sw = (r >> 1) & 7;
;   int foff[4];
; #pragma unroll
;   for (int ks = 0; ks < 4; ++ks) foff[ks] = r * 128 + (((2 * ks + h) ^ sw) << 4);
;   bf8 af[2][MB], bfr[2][2];
;   {
;     const char* as0 = As + wm * (32 * MB) * 128;
;     const char* bs0 = Bs + wn * 64 * 128;
; #pragma unroll
;     for (int mb = 0; mb < MB; ++mb) af[0][mb] = *(const bf8*)(as0 + mb * 32 * 128 + foff[0]);
; #pragma unroll
;     for (int nb = 0; nb < 2; ++nb) bfr[0][nb] = *(const bf8*)(bs0 + nb * 32 * 128 + foff[0]);
;   }
;   const int kbase = rot % KT;
;   if (KT > 1) {
;     const int k1_ = (kbase + 1 >= KT) ? kbase + 1 - KT : kbase + 1;
;     const int ko_ = k1_ * 64;
; #pragma unroll
;     for (int pc = 0; pc < 3; ++pc) GEMM_PIECE(1, pc)
;   }
;   DI void operator()(f32x16 (&acc)[2][4], int wm, int wn, int r, int h) {
;     ...
;             const int ff = nt * 128 + wn * 32 + crow(i0, h) + nb * DFF;
;             const f32x2n a0 = *(const f32x2n*)(cw + ff), a1 = *(const f32x2n*)(cw + 2 * DFF + ff), a2 = *(const f32x2n*)(cw + 4 * DFF + ff),
;                          a3 = *(const f32x2n*)(cb + ff);
;             w0[0] = a0.x; w0[1] = a0.y; w1[0] = a1.x; w1[1] = a1.y; w2[0] = a2.x; w2[1] = a2.y; bz[0] = a3.x; bz[1] = a3.y;
.Lupd_7:
	s_lshl_b32 s2, s16, 13
	s_lshl_b32 s17, s15, 14
	s_bitset1_b32 s2, 16
	s_add_i32 s25, s28, 64
	v_lshrrev_b32_e32 v5, 5, v165
	v_and_b32_e32 v167, 31, v165
	v_bfe_u32 v2, v165, 1, 3
	s_cmp_lt_i32 s19, 15
	v_lshlrev_b32_e32 v3, 7, v167
	v_bitop3_b32 v5, v5, v2, 1 bitop3:0x6c
	s_cselect_b32 s28, s25, 0
	v_lshl_or_b32 v5, v5, 4, v3
	s_ashr_i32 s29, s28, 31
	v_bfe_u32 v169, v165, 5, 1
	v_or_b32_e32 v164, s17, v5
	s_lshl_b64 s[28:29], s[28:29], 1
	s_cmp_eq_u32 s38, 0
	s_cbranch_scc1 .Lupd_w0
	s_waitcnt vmcnt(0)
.Lupd_w0:
	s_barrier
	v_bitop3_b32 v7, v169, v2, 2 bitop3:0x36
	ds_read_b128 v[146:149], v164
	ds_read_b128 v[142:145], v164 offset:4096
	ds_read_b128 v[134:137], v164 offset:8192
	ds_read_b128 v[130:133], v164 offset:12288
	s_add_u32 s28, s84, s28
	v_lshl_or_b32 v171, v7, 4, v3
	v_bitop3_b32 v7, v169, v2, 4 bitop3:0x36
	v_bitop3_b32 v2, v169, v2, 6 bitop3:0x36
	v_or_b32_e32 v166, s2, v5
	s_addc_u32 s29, s85, s29
	v_lshl_or_b32 v170, v7, 4, v3
	v_lshl_or_b32 v168, v2, 4, v3
	ds_read_b128 v[150:153], v166
	ds_read_b128 v[138:141], v166 offset:4096
	s_lshl_b32 s100, s48, 9
	s_lshl_b32 s101, s16, 7
	s_add_i32 s100, s100, s101
	v_lshlrev_b32_e32 v248, 2, v167
	v_add_u32_e32 v248, s100, v248
	v_add_u32_e32 v249, 0x2c00, v248
	global_load_dword v241, v248, s[40:41]
	global_load_dword v240, v248, s[44:45]
	global_load_dword v243, v248, s[46:47]
	global_load_dword v242, v248, s[42:43]
	global_load_dword v245, v249, s[40:41]
	global_load_dword v244, v249, s[44:45]
	global_load_dword v247, v249, s[46:47]
	global_load_dword v246, v249, s[42:43]
	s_add_i32 s25, s3, 0x8000
	v_lshl_add_u64 v[2:3], s[28:29], 0, v[0:1]
	s_mov_b32 m0, s25
	s_nop 0
	global_load_lds_dwordx4 v[2:3], off
	v_lshl_add_u64 v[2:3], s[28:29], 0, v[10:11]
	s_add_i32 s25, s3, 0xa000
	s_mov_b32 m0, s25
	s_nop 0
	global_load_lds_dwordx4 v[2:3], off
	v_lshl_add_u64 v[2:3], s[28:29], 0, v[12:13]
	s_add_i32 s25, s3, 0xc000
	s_mov_b32 m0, s25
	s_nop 0
	global_load_lds_dwordx4 v[2:3], off
	v_mov_b32_e32 v2, 0
	s_mov_b32 s18, 0
	v_lshl_add_u64 v[156:157], s[84:85], 0, v[14:15]
	v_lshlrev_b32_e32 v0, 1, v4
	v_lshlrev_b32_e32 v158, 1, v6
	v_lshlrev_b32_e32 v160, 1, v8
	s_mov_b32 s25, s19
	v_mov_b32_e32 v3, v2
	v_mov_b32_e32 v4, v2
	v_mov_b32_e32 v5, v2
	v_mov_b32_e32 v6, v2
	v_mov_b32_e32 v7, v2
	v_mov_b32_e32 v8, v2
	v_mov_b32_e32 v9, v2
	v_mov_b32_e32 v10, v2
	v_mov_b32_e32 v11, v2
	v_mov_b32_e32 v12, v2
	v_mov_b32_e32 v13, v2
	v_mov_b32_e32 v14, v2
	v_mov_b32_e32 v15, v2
	v_mov_b32_e32 v16, v2
	v_mov_b32_e32 v17, v2
	v_mov_b32_e32 v18, v2
	v_mov_b32_e32 v19, v2
	v_mov_b32_e32 v20, v2
	v_mov_b32_e32 v21, v2
	v_mov_b32_e32 v22, v2
	v_mov_b32_e32 v23, v2
	v_mov_b32_e32 v24, v2
	v_mov_b32_e32 v25, v2
	v_mov_b32_e32 v26, v2
	v_mov_b32_e32 v27, v2
	v_mov_b32_e32 v28, v2
	v_mov_b32_e32 v29, v2
	v_mov_b32_e32 v30, v2
	v_mov_b32_e32 v31, v2
	v_mov_b32_e32 v32, v2
	v_mov_b32_e32 v33, v2
	v_mov_b32_e32 v50, v2
	v_mov_b32_e32 v51, v2
	v_mov_b32_e32 v52, v2
	v_mov_b32_e32 v53, v2
	v_mov_b32_e32 v54, v2
	v_mov_b32_e32 v55, v2
	v_mov_b32_e32 v56, v2
	v_mov_b32_e32 v57, v2
	v_mov_b32_e32 v58, v2
	v_mov_b32_e32 v59, v2
	v_mov_b32_e32 v60, v2
	v_mov_b32_e32 v61, v2
	v_mov_b32_e32 v62, v2
	v_mov_b32_e32 v63, v2
	v_mov_b32_e32 v64, v2
	v_mov_b32_e32 v65, v2
	v_mov_b32_e32 v98, v2
	v_mov_b32_e32 v99, v2
	v_mov_b32_e32 v100, v2
	v_mov_b32_e32 v101, v2
	v_mov_b32_e32 v102, v2
	v_mov_b32_e32 v103, v2
	v_mov_b32_e32 v104, v2
	v_mov_b32_e32 v105, v2
	v_mov_b32_e32 v106, v2
	v_mov_b32_e32 v107, v2
	v_mov_b32_e32 v108, v2
	v_mov_b32_e32 v109, v2
	v_mov_b32_e32 v110, v2
	v_mov_b32_e32 v111, v2
	v_mov_b32_e32 v112, v2
	v_mov_b32_e32 v113, v2
	v_mov_b32_e32 v114, v2
	v_mov_b32_e32 v115, v2
	v_mov_b32_e32 v116, v2
	v_mov_b32_e32 v117, v2
	v_mov_b32_e32 v118, v2
	v_mov_b32_e32 v119, v2
	v_mov_b32_e32 v120, v2
	v_mov_b32_e32 v121, v2
	v_mov_b32_e32 v122, v2
	v_mov_b32_e32 v123, v2
	v_mov_b32_e32 v124, v2
	v_mov_b32_e32 v125, v2
	v_mov_b32_e32 v126, v2
	v_mov_b32_e32 v127, v2
	v_mov_b32_e32 v128, v2
	v_mov_b32_e32 v129, v2
	v_mov_b32_e32 v82, v2
	v_mov_b32_e32 v83, v2
	v_mov_b32_e32 v84, v2
	v_mov_b32_e32 v85, v2
	v_mov_b32_e32 v86, v2
	v_mov_b32_e32 v87, v2
	v_mov_b32_e32 v88, v2
	v_mov_b32_e32 v89, v2
	v_mov_b32_e32 v90, v2
	v_mov_b32_e32 v91, v2
	v_mov_b32_e32 v92, v2
	v_mov_b32_e32 v93, v2
	v_mov_b32_e32 v94, v2
	v_mov_b32_e32 v95, v2
	v_mov_b32_e32 v96, v2
	v_mov_b32_e32 v97, v2
	v_mov_b32_e32 v66, v2
	v_mov_b32_e32 v67, v2
	v_mov_b32_e32 v68, v2
	v_mov_b32_e32 v69, v2
	v_mov_b32_e32 v70, v2
	v_mov_b32_e32 v71, v2
	v_mov_b32_e32 v72, v2
	v_mov_b32_e32 v73, v2
	v_mov_b32_e32 v74, v2
	v_mov_b32_e32 v75, v2
	v_mov_b32_e32 v76, v2
	v_mov_b32_e32 v77, v2
	v_mov_b32_e32 v78, v2
	v_mov_b32_e32 v79, v2
	v_mov_b32_e32 v80, v2
	v_mov_b32_e32 v81, v2
	v_mov_b32_e32 v34, v2
	v_mov_b32_e32 v35, v2
	v_mov_b32_e32 v36, v2
	v_mov_b32_e32 v37, v2
	v_mov_b32_e32 v38, v2
	v_mov_b32_e32 v39, v2
	v_mov_b32_e32 v40, v2
	v_mov_b32_e32 v41, v2
	v_mov_b32_e32 v42, v2
	v_mov_b32_e32 v43, v2
	v_mov_b32_e32 v44, v2
	v_mov_b32_e32 v45, v2
	v_mov_b32_e32 v46, v2
	v_mov_b32_e32 v47, v2
	v_mov_b32_e32 v48, v2
	v_mov_b32_e32 v49, v2

;   DI void operator()(f32x16 (&acc)[2][4], int wm, int wn, int r, int h) {
;     ...
;     asm volatile("s_waitcnt lgkmcnt(0)" ::: "memory");
;     const int lane = h * 32 + r;
; #pragma unroll
;     for (int j = 0; j < 8; ++j) {
;       const int tk = (lane >> 2) + 16 * j, ch = lane & 3;
;       const int tr = wm * 128 + tk;
;       const int R = row0 + tr;
;       const u32x4 v = *(const u32x4*)(ost + tk * 40 + ch * 8);
;       if ((tr >= 1) && (tr <= 254) && (R >= 0) && (R < Mrows))
;         *(u32x4*)(act + (size_t)R * DFF + nt * 128 + wn * 32 + ch * 8) = v;
;     }
.Lupe_done:
	s_cmp_eq_u32 s101, 1
	s_cselect_b64 s[38:39], 0, -1
	v_bfe_u32 v188, v165, 2, 4
	v_bfe_u32 v189, v188, 2, 1
	v_xor_b32_e32 v189, v189, v188
	v_and_b32_e32 v190, 3, v165
	v_lshlrev_b32_e32 v189, 6, v189
	v_lshl_add_u32 v189, v190, 4, v189
	v_add_u32_e32 v189, s0, v189
	s_waitcnt lgkmcnt(0)
	ds_read_b128 v[130:133], v189 offset:0
	ds_read_b128 v[134:137], v189 offset:1024
	ds_read_b128 v[138:141], v189 offset:2048
	ds_read_b128 v[142:145], v189 offset:3072
	ds_read_b128 v[146:149], v189 offset:4096
	ds_read_b128 v[150:153], v189 offset:5120
	ds_read_b128 v[154:157], v189 offset:6144
	ds_read_b128 v[158:161], v189 offset:7168
	s_lshl_b32 s2, s15, 7
	v_add_u32_e32 v191, s2, v188
	v_add_u32_e32 v192, s14, v191
	s_lshl_b32 s3, s48, 7
	s_lshl_b32 s2, s16, 5
	s_add_i32 s3, s3, s2
	v_lshl_add_u32 v193, v190, 3, s3
	v_lshlrev_b32_e32 v193, 1, v193
	s_movk_i32 s2, 0x1600
	v_mad_u32_u24 v193, v192, s2, v193
	v_cmp_eq_u32_e32 vcc, 0, v191
	s_nop 1
	v_cndmask_b32_e64 v194, v192, -1, vcc
	v_cmp_gt_u32_e32 vcc, s26, v194
	s_waitcnt vmcnt(0)
	s_and_saveexec_b64 s[2:3], vcc
	s_waitcnt lgkmcnt(7)
	global_store_dwordx4 v193, v[130:133], s[20:21]
	s_mov_b64 exec, -1
	v_add_u32_e32 v194, 16, v192
	v_cmp_gt_u32_e32 vcc, s26, v194
	s_and_saveexec_b64 s[2:3], vcc
	s_waitcnt lgkmcnt(6)
	v_add_u32_e32 v195, 0x16000, v193
	global_store_dwordx4 v195, v[134:137], s[20:21]
	s_mov_b64 exec, -1
	v_add_u32_e32 v194, 32, v192
	v_cmp_gt_u32_e32 vcc, s26, v194
	s_and_saveexec_b64 s[2:3], vcc
	s_waitcnt lgkmcnt(5)
	v_add_u32_e32 v195, 0x2c000, v193
	global_store_dwordx4 v195, v[138:141], s[20:21]
	s_mov_b64 exec, -1
	v_add_u32_e32 v194, 48, v192
	v_cmp_gt_u32_e32 vcc, s26, v194
	s_and_saveexec_b64 s[2:3], vcc
	s_waitcnt lgkmcnt(4)
	v_add_u32_e32 v195, 0x42000, v193
	global_store_dwordx4 v195, v[142:145], s[20:21]
	s_mov_b64 exec, -1
	v_add_u32_e32 v194, 64, v192
	v_cmp_gt_u32_e32 vcc, s26, v194
	s_and_saveexec_b64 s[2:3], vcc
	s_waitcnt lgkmcnt(3)
	v_add_u32_e32 v195, 0x58000, v193
	global_store_dwordx4 v195, v[146:149], s[20:21]
	s_mov_b64 exec, -1
	v_add_u32_e32 v194, 80, v192
	v_cmp_gt_u32_e32 vcc, s26, v194
	s_and_saveexec_b64 s[2:3], vcc
	s_waitcnt lgkmcnt(2)
	v_add_u32_e32 v195, 0x6e000, v193
	global_store_dwordx4 v195, v[150:153], s[20:21]
	s_mov_b64 exec, -1
	v_add_u32_e32 v194, 96, v192
	v_cmp_gt_u32_e32 vcc, s26, v194
	s_and_saveexec_b64 s[2:3], vcc
	s_waitcnt lgkmcnt(1)
	v_add_u32_e32 v195, 0x84000, v193
	global_store_dwordx4 v195, v[154:157], s[20:21]
	s_mov_b64 exec, -1
	v_add_u32_e32 v194, 112, v192
	v_add_u32_e32 v195, 0x70, v191
	v_cmp_eq_u32_e32 vcc, 0xff, v195
	s_nop 1
	v_cndmask_b32_e64 v194, v194, -1, vcc
	v_cmp_gt_u32_e32 vcc, s26, v194
	s_and_saveexec_b64 s[2:3], vcc
	s_waitcnt lgkmcnt(0)
	v_add_u32_e32 v195, 0x9a000, v193
	global_store_dwordx4 v195, v[158:161], s[20:21]
	s_mov_b64 exec, -1
	s_branch .LBB0_771
